# grid-barrier spin loops poll with s_sleep 0 instead of s_sleep 1
# speedup vs baseline: 1.0056x; 1.0030x over previous
; __device__ __forceinline__ unsigned xb_ld(unsigned* p)              { return __hip_atomic_load(p, __ATOMIC_RELAXED, __HIP_MEMORY_SCOPE_AGENT); }
; __device__ __forceinline__ void xcd_barrier_complete(unsigned* bar, unsigned x, unsigned& nloc, unsigned& nx) {
;     const unsigned G = gridDim.x * gridDim.y * gridDim.z;
;     unsigned sum, cnt, mine, sp = 0u;
;     for (;;) {
;         sum = 0u; cnt = 0u; mine = 0u;
; #pragma unroll
;         for (unsigned j = 0; j < 16; ++j) { const unsigned c = xb_ld(&bar[XB_XCNT(j)]); sum += c; cnt += (c > 0u) ? 1u : 0u; mine = (j == x) ? c : mine; }
;         if (sum == G) break;
;         __builtin_amdgcn_s_sleep(1);
;         if ((++sp & 255u) == 0u) { if (xb_ld(&bar[XB_TMO])) break; if (sp > XB_SPIN_CAP) { atomicAdd(&bar[XB_TMO], 1u); break; } }
.LBB0_82:
	global_load_dword v16, v17, s[6:7] sc1
	global_load_dword v1, v17, s[30:31] sc1
	global_load_dword v2, v17, s[40:41] sc1
	global_load_dword v3, v17, s[50:51] sc1
	global_load_dword v4, v17, s[52:53] sc1
	global_load_dword v5, v17, s[54:55] sc1
	global_load_dword v6, v17, s[56:57] sc1
	global_load_dword v7, v17, s[58:59] sc1
	global_load_dword v8, v17, s[60:61] sc1
	global_load_dword v9, v17, s[62:63] sc1
	global_load_dword v10, v17, s[64:65] sc1
	global_load_dword v11, v17, s[66:67] sc1
	global_load_dword v12, v17, s[68:69] sc1
	global_load_dword v13, v17, s[70:71] sc1
	global_load_dword v14, v17, s[72:73] sc1
	global_load_dword v15, v17, s[74:75] sc1
	s_mov_b64 s[76:77], -1
	s_mov_b64 s[78:79], -1
	s_waitcnt vmcnt(14)
	v_add_u32_e32 v18, v1, v16
	s_waitcnt vmcnt(13)
	v_add_u32_e32 v18, v18, v2
	s_waitcnt vmcnt(12)
	v_add_u32_e32 v18, v18, v3
	s_waitcnt vmcnt(11)
	v_add_u32_e32 v18, v18, v4
	s_waitcnt vmcnt(10)
	v_add_u32_e32 v18, v18, v5
	s_waitcnt vmcnt(9)
	v_add_u32_e32 v18, v18, v6
	s_waitcnt vmcnt(8)
	v_add_u32_e32 v18, v18, v7
	s_waitcnt vmcnt(7)
	v_add_u32_e32 v18, v18, v8
	s_waitcnt vmcnt(6)
	v_add_u32_e32 v18, v18, v9
	s_waitcnt vmcnt(5)
	v_add_u32_e32 v18, v18, v10
	s_waitcnt vmcnt(4)
	v_add_u32_e32 v18, v18, v11
	s_waitcnt vmcnt(3)
	v_add_u32_e32 v18, v18, v12
	s_waitcnt vmcnt(2)
	v_add_u32_e32 v18, v18, v13
	s_waitcnt vmcnt(1)
	v_add_u32_e32 v18, v18, v14
	s_waitcnt vmcnt(0)
	v_add_u32_e32 v18, v18, v15
	v_cmp_eq_u32_e32 vcc, s0, v18
	s_cbranch_vccnz .LBB0_81
	s_and_b32 s9, s1, 0xff
	s_cmp_eq_u32 s9, 0
	s_mov_b64 s[80:81], -1
	s_sleep 0
	s_cbranch_scc1 .LBB0_86
	s_and_b64 vcc, exec, s[80:81]
	s_cbranch_vccz .LBB0_81

; __device__ __forceinline__ unsigned xb_ld(unsigned* p)              { return __hip_atomic_load(p, __ATOMIC_RELAXED, __HIP_MEMORY_SCOPE_AGENT); }
; __device__ __forceinline__ unsigned xb_add(unsigned* p, unsigned v) { return __hip_atomic_fetch_add(p, v, __ATOMIC_RELAXED, __HIP_MEMORY_SCOPE_AGENT); }
; #define XB_SPIN(cond, bar) do { unsigned _sp = 0; while (cond) { __builtin_amdgcn_s_sleep(1); \
;     if ((++_sp & 255u) == 0u) { if (xb_ld(&(bar)[XB_TMO])) break; if (_sp > XB_SPIN_CAP) { atomicAdd(&(bar)[XB_TMO], 1u); break; } } } } while (0)
; __device__ __forceinline__ void xcd_barrier(const XcdBarrier& b) {
;     ...
;             const unsigned tg = og / nx;
;             if (og + 1u == (tg + 1u) * nx) xb_add(&bar[XB_TOPGEN], 1u);
;             else XB_SPIN(xb_ld(&bar[XB_TOPGEN]) == tg, bar);
;             __builtin_amdgcn_fence(__ATOMIC_ACQUIRE, "agent");
;             xb_add(&bar[XB_XGEN(b.x)], 1u);
;             asm volatile("s_waitcnt vmcnt(0)" ::: "memory");
;         } else {
;             XB_SPIN(xb_ld(&bar[XB_XGEN(b.x)]) == gen, bar);
;             __builtin_amdgcn_fence(__ATOMIC_ACQUIRE, "agent");
;             asm volatile("s_waitcnt vmcnt(0)" ::: "memory");
;         }
.LBB0_100:
	s_and_b32 s1, s0, 0xff
	s_mov_b64 s[56:57], -1
	s_cmp_lg_u32 s1, 0
	s_mov_b64 s[60:61], -1
	s_sleep 0
	s_cbranch_scc0 .LBB0_103
	s_and_b64 vcc, exec, s[60:61]
	s_cbranch_vccz .LBB0_99

; __device__ __forceinline__ unsigned xb_ld(unsigned* p)              { return __hip_atomic_load(p, __ATOMIC_RELAXED, __HIP_MEMORY_SCOPE_AGENT); }
; __device__ __forceinline__ unsigned xb_add(unsigned* p, unsigned v) { return __hip_atomic_fetch_add(p, v, __ATOMIC_RELAXED, __HIP_MEMORY_SCOPE_AGENT); }
; #define XB_SPIN(cond, bar) do { unsigned _sp = 0; while (cond) { __builtin_amdgcn_s_sleep(1); \
;     if ((++_sp & 255u) == 0u) { if (xb_ld(&(bar)[XB_TMO])) break; if (_sp > XB_SPIN_CAP) { atomicAdd(&(bar)[XB_TMO], 1u); break; } } } } while (0)
; __device__ __forceinline__ void xcd_barrier(const XcdBarrier& b) {
;     ...
;             const unsigned tg = og / nx;
;             if (og + 1u == (tg + 1u) * nx) xb_add(&bar[XB_TOPGEN], 1u);
;             else XB_SPIN(xb_ld(&bar[XB_TOPGEN]) == tg, bar);
;             __builtin_amdgcn_fence(__ATOMIC_ACQUIRE, "agent");
;             xb_add(&bar[XB_XGEN(b.x)], 1u);
;             asm volatile("s_waitcnt vmcnt(0)" ::: "memory");
;         } else {
;             XB_SPIN(xb_ld(&bar[XB_XGEN(b.x)]) == gen, bar);
;             __builtin_amdgcn_fence(__ATOMIC_ACQUIRE, "agent");
;             asm volatile("s_waitcnt vmcnt(0)" ::: "memory");
;         }
.LBB0_117:
	s_and_b32 s1, s0, 0xff
	s_cmp_lg_u32 s1, 0
	s_mov_b64 s[58:59], -1
	s_sleep 0
	s_cbranch_scc0 .LBB0_120
	s_mov_b64 s[60:61], -1
	s_and_b64 vcc, exec, s[58:59]
	s_cbranch_vccz .LBB0_116

; __device__ __forceinline__ unsigned xb_ld(unsigned* p)              { return __hip_atomic_load(p, __ATOMIC_RELAXED, __HIP_MEMORY_SCOPE_AGENT); }
; __device__ __forceinline__ void xcd_barrier_complete(unsigned* bar, unsigned x, unsigned& nloc, unsigned& nx) {
;     const unsigned G = gridDim.x * gridDim.y * gridDim.z;
;     unsigned sum, cnt, mine, sp = 0u;
;     for (;;) {
;         sum = 0u; cnt = 0u; mine = 0u;
; #pragma unroll
;         for (unsigned j = 0; j < 16; ++j) { const unsigned c = xb_ld(&bar[XB_XCNT(j)]); sum += c; cnt += (c > 0u) ? 1u : 0u; mine = (j == x) ? c : mine; }
;         if (sum == G) break;
;         __builtin_amdgcn_s_sleep(1);
;         if ((++sp & 255u) == 0u) { if (xb_ld(&bar[XB_TMO])) break; if (sp > XB_SPIN_CAP) { atomicAdd(&bar[XB_TMO], 1u); break; } }
.LBB0_465:
	global_load_dword v16, v17, s[6:7] sc1
	global_load_dword v1, v17, s[16:17] sc1
	global_load_dword v2, v17, s[18:19] sc1
	global_load_dword v3, v17, s[20:21] sc1
	global_load_dword v4, v17, s[34:35] sc1
	global_load_dword v5, v17, s[40:41] sc1
	global_load_dword v6, v17, s[44:45] sc1
	global_load_dword v7, v17, s[46:47] sc1
	global_load_dword v8, v17, s[50:51] sc1
	global_load_dword v9, v17, s[52:53] sc1
	global_load_dword v10, v17, s[54:55] sc1
	global_load_dword v11, v17, s[56:57] sc1
	global_load_dword v12, v17, s[58:59] sc1
	global_load_dword v13, v17, s[60:61] sc1
	global_load_dword v14, v17, s[62:63] sc1
	global_load_dword v15, v17, s[64:65] sc1
	s_mov_b64 s[66:67], -1
	s_mov_b64 s[68:69], -1
	s_waitcnt vmcnt(14)
	v_add_u32_e32 v18, v1, v16
	s_waitcnt vmcnt(13)
	v_add_u32_e32 v18, v18, v2
	s_waitcnt vmcnt(12)
	v_add_u32_e32 v18, v18, v3
	s_waitcnt vmcnt(11)
	v_add_u32_e32 v18, v18, v4
	s_waitcnt vmcnt(10)
	v_add_u32_e32 v18, v18, v5
	s_waitcnt vmcnt(9)
	v_add_u32_e32 v18, v18, v6
	s_waitcnt vmcnt(8)
	v_add_u32_e32 v18, v18, v7
	s_waitcnt vmcnt(7)
	v_add_u32_e32 v18, v18, v8
	s_waitcnt vmcnt(6)
	v_add_u32_e32 v18, v18, v9
	s_waitcnt vmcnt(5)
	v_add_u32_e32 v18, v18, v10
	s_waitcnt vmcnt(4)
	v_add_u32_e32 v18, v18, v11
	s_waitcnt vmcnt(3)
	v_add_u32_e32 v18, v18, v12
	s_waitcnt vmcnt(2)
	v_add_u32_e32 v18, v18, v13
	s_waitcnt vmcnt(1)
	v_add_u32_e32 v18, v18, v14
	s_waitcnt vmcnt(0)
	v_add_u32_e32 v18, v18, v15
	v_cmp_eq_u32_e32 vcc, s0, v18
	s_cbranch_vccnz .LBB0_464
	s_and_b32 s9, s1, 0xff
	s_cmp_eq_u32 s9, 0
	s_mov_b64 s[70:71], -1
	s_sleep 0
	s_cbranch_scc1 .LBB0_469
	s_and_b64 vcc, exec, s[70:71]
	s_cbranch_vccz .LBB0_464

; __device__ __forceinline__ unsigned xb_ld(unsigned* p)              { return __hip_atomic_load(p, __ATOMIC_RELAXED, __HIP_MEMORY_SCOPE_AGENT); }
; __device__ __forceinline__ unsigned xb_add(unsigned* p, unsigned v) { return __hip_atomic_fetch_add(p, v, __ATOMIC_RELAXED, __HIP_MEMORY_SCOPE_AGENT); }
; #define XB_SPIN(cond, bar) do { unsigned _sp = 0; while (cond) { __builtin_amdgcn_s_sleep(1); \
;     if ((++_sp & 255u) == 0u) { if (xb_ld(&(bar)[XB_TMO])) break; if (_sp > XB_SPIN_CAP) { atomicAdd(&(bar)[XB_TMO], 1u); break; } } } } while (0)
; __device__ __forceinline__ void xcd_barrier(const XcdBarrier& b) {
;     ...
;             const unsigned tg = og / nx;
;             if (og + 1u == (tg + 1u) * nx) xb_add(&bar[XB_TOPGEN], 1u);
;             else XB_SPIN(xb_ld(&bar[XB_TOPGEN]) == tg, bar);
;             __builtin_amdgcn_fence(__ATOMIC_ACQUIRE, "agent");
;             xb_add(&bar[XB_XGEN(b.x)], 1u);
;             asm volatile("s_waitcnt vmcnt(0)" ::: "memory");
;         } else {
;             XB_SPIN(xb_ld(&bar[XB_XGEN(b.x)]) == gen, bar);
;             __builtin_amdgcn_fence(__ATOMIC_ACQUIRE, "agent");
;             asm volatile("s_waitcnt vmcnt(0)" ::: "memory");
;         }
.LBB0_483:
	s_and_b32 s1, s0, 0xff
	s_mov_b64 s[44:45], -1
	s_cmp_lg_u32 s1, 0
	s_mov_b64 s[50:51], -1
	s_sleep 0
	s_cbranch_scc0 .LBB0_486
	s_and_b64 vcc, exec, s[50:51]
	s_cbranch_vccz .LBB0_482

; __device__ __forceinline__ unsigned xb_ld(unsigned* p)              { return __hip_atomic_load(p, __ATOMIC_RELAXED, __HIP_MEMORY_SCOPE_AGENT); }
; __device__ __forceinline__ unsigned xb_add(unsigned* p, unsigned v) { return __hip_atomic_fetch_add(p, v, __ATOMIC_RELAXED, __HIP_MEMORY_SCOPE_AGENT); }
; #define XB_SPIN(cond, bar) do { unsigned _sp = 0; while (cond) { __builtin_amdgcn_s_sleep(1); \
;     if ((++_sp & 255u) == 0u) { if (xb_ld(&(bar)[XB_TMO])) break; if (_sp > XB_SPIN_CAP) { atomicAdd(&(bar)[XB_TMO], 1u); break; } } } } while (0)
; __device__ __forceinline__ void xcd_barrier(const XcdBarrier& b) {
;     ...
;             const unsigned tg = og / nx;
;             if (og + 1u == (tg + 1u) * nx) xb_add(&bar[XB_TOPGEN], 1u);
;             else XB_SPIN(xb_ld(&bar[XB_TOPGEN]) == tg, bar);
;             __builtin_amdgcn_fence(__ATOMIC_ACQUIRE, "agent");
;             xb_add(&bar[XB_XGEN(b.x)], 1u);
;             asm volatile("s_waitcnt vmcnt(0)" ::: "memory");
;         } else {
;             XB_SPIN(xb_ld(&bar[XB_XGEN(b.x)]) == gen, bar);
;             __builtin_amdgcn_fence(__ATOMIC_ACQUIRE, "agent");
;             asm volatile("s_waitcnt vmcnt(0)" ::: "memory");
;         }
.LBB0_500:
	s_and_b32 s1, s0, 0xff
	s_cmp_lg_u32 s1, 0
	s_mov_b64 s[46:47], -1
	s_sleep 0
	s_cbranch_scc0 .LBB0_503
	s_mov_b64 s[50:51], -1
	s_and_b64 vcc, exec, s[46:47]
	s_cbranch_vccz .LBB0_499

; __device__ __forceinline__ unsigned xb_ld(unsigned* p)              { return __hip_atomic_load(p, __ATOMIC_RELAXED, __HIP_MEMORY_SCOPE_AGENT); }
; __device__ __forceinline__ void xcd_barrier_complete(unsigned* bar, unsigned x, unsigned& nloc, unsigned& nx) {
;     const unsigned G = gridDim.x * gridDim.y * gridDim.z;
;     unsigned sum, cnt, mine, sp = 0u;
;     for (;;) {
;         sum = 0u; cnt = 0u; mine = 0u;
; #pragma unroll
;         for (unsigned j = 0; j < 16; ++j) { const unsigned c = xb_ld(&bar[XB_XCNT(j)]); sum += c; cnt += (c > 0u) ? 1u : 0u; mine = (j == x) ? c : mine; }
;         if (sum == G) break;
;         __builtin_amdgcn_s_sleep(1);
;         if ((++sp & 255u) == 0u) { if (xb_ld(&bar[XB_TMO])) break; if (sp > XB_SPIN_CAP) { atomicAdd(&bar[XB_TMO], 1u); break; } }
.LBB0_641:
	global_load_dword v16, v17, s[16:17] sc1
	global_load_dword v1, v17, s[18:19] sc1
	global_load_dword v2, v17, s[20:21] sc1
	global_load_dword v3, v17, s[34:35] sc1
	global_load_dword v4, v17, s[40:41] sc1
	global_load_dword v5, v17, s[44:45] sc1
	global_load_dword v6, v17, s[46:47] sc1
	global_load_dword v7, v17, s[50:51] sc1
	global_load_dword v8, v17, s[52:53] sc1
	global_load_dword v9, v17, s[54:55] sc1
	global_load_dword v10, v17, s[56:57] sc1
	global_load_dword v11, v17, s[58:59] sc1
	global_load_dword v12, v17, s[60:61] sc1
	global_load_dword v13, v17, s[62:63] sc1
	global_load_dword v14, v17, s[64:65] sc1
	global_load_dword v15, v17, s[66:67] sc1
	s_mov_b64 s[68:69], -1
	s_mov_b64 s[70:71], -1
	s_waitcnt vmcnt(14)
	v_add_u32_e32 v18, v1, v16
	s_waitcnt vmcnt(13)
	v_add_u32_e32 v18, v18, v2
	s_waitcnt vmcnt(12)
	v_add_u32_e32 v18, v18, v3
	s_waitcnt vmcnt(11)
	v_add_u32_e32 v18, v18, v4
	s_waitcnt vmcnt(10)
	v_add_u32_e32 v18, v18, v5
	s_waitcnt vmcnt(9)
	v_add_u32_e32 v18, v18, v6
	s_waitcnt vmcnt(8)
	v_add_u32_e32 v18, v18, v7
	s_waitcnt vmcnt(7)
	v_add_u32_e32 v18, v18, v8
	s_waitcnt vmcnt(6)
	v_add_u32_e32 v18, v18, v9
	s_waitcnt vmcnt(5)
	v_add_u32_e32 v18, v18, v10
	s_waitcnt vmcnt(4)
	v_add_u32_e32 v18, v18, v11
	s_waitcnt vmcnt(3)
	v_add_u32_e32 v18, v18, v12
	s_waitcnt vmcnt(2)
	v_add_u32_e32 v18, v18, v13
	s_waitcnt vmcnt(1)
	v_add_u32_e32 v18, v18, v14
	s_waitcnt vmcnt(0)
	v_add_u32_e32 v18, v18, v15
	v_cmp_eq_u32_e32 vcc, s0, v18
	s_cbranch_vccnz .LBB0_640
	s_and_b32 s10, s1, 0xff
	s_cmp_eq_u32 s10, 0
	s_mov_b64 s[72:73], -1
	s_sleep 0
	s_cbranch_scc1 .LBB0_645
	s_and_b64 vcc, exec, s[72:73]
	s_cbranch_vccz .LBB0_640

; __device__ __forceinline__ unsigned xb_ld(unsigned* p)              { return __hip_atomic_load(p, __ATOMIC_RELAXED, __HIP_MEMORY_SCOPE_AGENT); }
; __device__ __forceinline__ unsigned xb_add(unsigned* p, unsigned v) { return __hip_atomic_fetch_add(p, v, __ATOMIC_RELAXED, __HIP_MEMORY_SCOPE_AGENT); }
; #define XB_SPIN(cond, bar) do { unsigned _sp = 0; while (cond) { __builtin_amdgcn_s_sleep(1); \
;     if ((++_sp & 255u) == 0u) { if (xb_ld(&(bar)[XB_TMO])) break; if (_sp > XB_SPIN_CAP) { atomicAdd(&(bar)[XB_TMO], 1u); break; } } } } while (0)
; __device__ __forceinline__ void xcd_barrier(const XcdBarrier& b) {
;     ...
;             const unsigned tg = og / nx;
;             if (og + 1u == (tg + 1u) * nx) xb_add(&bar[XB_TOPGEN], 1u);
;             else XB_SPIN(xb_ld(&bar[XB_TOPGEN]) == tg, bar);
;             __builtin_amdgcn_fence(__ATOMIC_ACQUIRE, "agent");
;             xb_add(&bar[XB_XGEN(b.x)], 1u);
;             asm volatile("s_waitcnt vmcnt(0)" ::: "memory");
;         } else {
;             XB_SPIN(xb_ld(&bar[XB_XGEN(b.x)]) == gen, bar);
;             __builtin_amdgcn_fence(__ATOMIC_ACQUIRE, "agent");
;             asm volatile("s_waitcnt vmcnt(0)" ::: "memory");
;         }
.LBB0_659:
	s_and_b32 s1, s0, 0xff
	s_mov_b64 s[46:47], -1
	s_cmp_lg_u32 s1, 0
	s_mov_b64 s[52:53], -1
	s_sleep 0
	s_cbranch_scc0 .LBB0_662
	s_and_b64 vcc, exec, s[52:53]
	s_cbranch_vccz .LBB0_658

; __device__ __forceinline__ unsigned xb_ld(unsigned* p)              { return __hip_atomic_load(p, __ATOMIC_RELAXED, __HIP_MEMORY_SCOPE_AGENT); }
; __device__ __forceinline__ unsigned xb_add(unsigned* p, unsigned v) { return __hip_atomic_fetch_add(p, v, __ATOMIC_RELAXED, __HIP_MEMORY_SCOPE_AGENT); }
; #define XB_SPIN(cond, bar) do { unsigned _sp = 0; while (cond) { __builtin_amdgcn_s_sleep(1); \
;     if ((++_sp & 255u) == 0u) { if (xb_ld(&(bar)[XB_TMO])) break; if (_sp > XB_SPIN_CAP) { atomicAdd(&(bar)[XB_TMO], 1u); break; } } } } while (0)
; __device__ __forceinline__ void xcd_barrier(const XcdBarrier& b) {
;     ...
;             const unsigned tg = og / nx;
;             if (og + 1u == (tg + 1u) * nx) xb_add(&bar[XB_TOPGEN], 1u);
;             else XB_SPIN(xb_ld(&bar[XB_TOPGEN]) == tg, bar);
;             __builtin_amdgcn_fence(__ATOMIC_ACQUIRE, "agent");
;             xb_add(&bar[XB_XGEN(b.x)], 1u);
;             asm volatile("s_waitcnt vmcnt(0)" ::: "memory");
;         } else {
;             XB_SPIN(xb_ld(&bar[XB_XGEN(b.x)]) == gen, bar);
;             __builtin_amdgcn_fence(__ATOMIC_ACQUIRE, "agent");
;             asm volatile("s_waitcnt vmcnt(0)" ::: "memory");
;         }
.LBB0_676:
	s_and_b32 s1, s0, 0xff
	s_cmp_lg_u32 s1, 0
	s_mov_b64 s[50:51], -1
	s_sleep 0
	s_cbranch_scc0 .LBB0_679
	s_mov_b64 s[52:53], -1
	s_and_b64 vcc, exec, s[50:51]
	s_cbranch_vccz .LBB0_675

; __device__ __forceinline__ unsigned xb_ld(unsigned* p)              { return __hip_atomic_load(p, __ATOMIC_RELAXED, __HIP_MEMORY_SCOPE_AGENT); }
; __device__ __forceinline__ void xcd_barrier_complete(unsigned* bar, unsigned x, unsigned& nloc, unsigned& nx) {
;     const unsigned G = gridDim.x * gridDim.y * gridDim.z;
;     unsigned sum, cnt, mine, sp = 0u;
;     for (;;) {
;         sum = 0u; cnt = 0u; mine = 0u;
; #pragma unroll
;         for (unsigned j = 0; j < 16; ++j) { const unsigned c = xb_ld(&bar[XB_XCNT(j)]); sum += c; cnt += (c > 0u) ? 1u : 0u; mine = (j == x) ? c : mine; }
;         if (sum == G) break;
;         __builtin_amdgcn_s_sleep(1);
;         if ((++sp & 255u) == 0u) { if (xb_ld(&bar[XB_TMO])) break; if (sp > XB_SPIN_CAP) { atomicAdd(&bar[XB_TMO], 1u); break; } }
.LBB0_746:
	global_load_dword v16, v17, s[16:17] sc1
	global_load_dword v1, v17, s[18:19] sc1
	global_load_dword v2, v17, s[20:21] sc1
	global_load_dword v3, v17, s[34:35] sc1
	global_load_dword v4, v17, s[40:41] sc1
	global_load_dword v5, v17, s[42:43] sc1
	global_load_dword v6, v17, s[44:45] sc1
	global_load_dword v7, v17, s[46:47] sc1
	global_load_dword v8, v17, s[48:49] sc1
	global_load_dword v9, v17, s[50:51] sc1
	global_load_dword v10, v17, s[52:53] sc1
	global_load_dword v11, v17, s[54:55] sc1
	global_load_dword v12, v17, s[56:57] sc1
	global_load_dword v13, v17, s[58:59] sc1
	global_load_dword v14, v17, s[60:61] sc1
	global_load_dword v15, v17, s[62:63] sc1
	s_mov_b64 s[64:65], -1
	s_mov_b64 s[66:67], -1
	s_waitcnt vmcnt(14)
	v_add_u32_e32 v18, v1, v16
	s_waitcnt vmcnt(13)
	v_add_u32_e32 v18, v18, v2
	s_waitcnt vmcnt(12)
	v_add_u32_e32 v18, v18, v3
	s_waitcnt vmcnt(11)
	v_add_u32_e32 v18, v18, v4
	s_waitcnt vmcnt(10)
	v_add_u32_e32 v18, v18, v5
	s_waitcnt vmcnt(9)
	v_add_u32_e32 v18, v18, v6
	s_waitcnt vmcnt(8)
	v_add_u32_e32 v18, v18, v7
	s_waitcnt vmcnt(7)
	v_add_u32_e32 v18, v18, v8
	s_waitcnt vmcnt(6)
	v_add_u32_e32 v18, v18, v9
	s_waitcnt vmcnt(5)
	v_add_u32_e32 v18, v18, v10
	s_waitcnt vmcnt(4)
	v_add_u32_e32 v18, v18, v11
	s_waitcnt vmcnt(3)
	v_add_u32_e32 v18, v18, v12
	s_waitcnt vmcnt(2)
	v_add_u32_e32 v18, v18, v13
	s_waitcnt vmcnt(1)
	v_add_u32_e32 v18, v18, v14
	s_waitcnt vmcnt(0)
	v_add_u32_e32 v18, v18, v15
	v_cmp_eq_u32_e32 vcc, s0, v18
	s_cbranch_vccnz .LBB0_745
	s_and_b32 s9, s1, 0xff
	s_cmp_eq_u32 s9, 0
	s_mov_b64 s[68:69], -1
	s_sleep 0
	s_cbranch_scc1 .LBB0_750
	s_and_b64 vcc, exec, s[68:69]
	s_cbranch_vccz .LBB0_745

; __device__ __forceinline__ unsigned xb_ld(unsigned* p)              { return __hip_atomic_load(p, __ATOMIC_RELAXED, __HIP_MEMORY_SCOPE_AGENT); }
; __device__ __forceinline__ unsigned xb_add(unsigned* p, unsigned v) { return __hip_atomic_fetch_add(p, v, __ATOMIC_RELAXED, __HIP_MEMORY_SCOPE_AGENT); }
; #define XB_SPIN(cond, bar) do { unsigned _sp = 0; while (cond) { __builtin_amdgcn_s_sleep(1); \
;     if ((++_sp & 255u) == 0u) { if (xb_ld(&(bar)[XB_TMO])) break; if (_sp > XB_SPIN_CAP) { atomicAdd(&(bar)[XB_TMO], 1u); break; } } } } while (0)
; __device__ __forceinline__ void xcd_barrier(const XcdBarrier& b) {
;     ...
;             const unsigned tg = og / nx;
;             if (og + 1u == (tg + 1u) * nx) xb_add(&bar[XB_TOPGEN], 1u);
;             else XB_SPIN(xb_ld(&bar[XB_TOPGEN]) == tg, bar);
;             __builtin_amdgcn_fence(__ATOMIC_ACQUIRE, "agent");
;             xb_add(&bar[XB_XGEN(b.x)], 1u);
;             asm volatile("s_waitcnt vmcnt(0)" ::: "memory");
;         } else {
;             XB_SPIN(xb_ld(&bar[XB_XGEN(b.x)]) == gen, bar);
;             __builtin_amdgcn_fence(__ATOMIC_ACQUIRE, "agent");
;             asm volatile("s_waitcnt vmcnt(0)" ::: "memory");
;         }
.LBB0_764:
	s_and_b32 s1, s0, 0xff
	s_mov_b64 s[44:45], -1
	s_cmp_lg_u32 s1, 0
	s_mov_b64 s[48:49], -1
	s_sleep 0
	s_cbranch_scc0 .LBB0_767
	s_and_b64 vcc, exec, s[48:49]
	s_cbranch_vccz .LBB0_763

; __device__ __forceinline__ unsigned xb_ld(unsigned* p)              { return __hip_atomic_load(p, __ATOMIC_RELAXED, __HIP_MEMORY_SCOPE_AGENT); }
; __device__ __forceinline__ unsigned xb_add(unsigned* p, unsigned v) { return __hip_atomic_fetch_add(p, v, __ATOMIC_RELAXED, __HIP_MEMORY_SCOPE_AGENT); }
; #define XB_SPIN(cond, bar) do { unsigned _sp = 0; while (cond) { __builtin_amdgcn_s_sleep(1); \
;     if ((++_sp & 255u) == 0u) { if (xb_ld(&(bar)[XB_TMO])) break; if (_sp > XB_SPIN_CAP) { atomicAdd(&(bar)[XB_TMO], 1u); break; } } } } while (0)
; __device__ __forceinline__ void xcd_barrier(const XcdBarrier& b) {
;     ...
;             const unsigned tg = og / nx;
;             if (og + 1u == (tg + 1u) * nx) xb_add(&bar[XB_TOPGEN], 1u);
;             else XB_SPIN(xb_ld(&bar[XB_TOPGEN]) == tg, bar);
;             __builtin_amdgcn_fence(__ATOMIC_ACQUIRE, "agent");
;             xb_add(&bar[XB_XGEN(b.x)], 1u);
;             asm volatile("s_waitcnt vmcnt(0)" ::: "memory");
;         } else {
;             XB_SPIN(xb_ld(&bar[XB_XGEN(b.x)]) == gen, bar);
;             __builtin_amdgcn_fence(__ATOMIC_ACQUIRE, "agent");
;             asm volatile("s_waitcnt vmcnt(0)" ::: "memory");
;         }
.LBB0_781:
	s_and_b32 s1, s0, 0xff
	s_cmp_lg_u32 s1, 0
	s_mov_b64 s[46:47], -1
	s_sleep 0
	s_cbranch_scc0 .LBB0_784
	s_mov_b64 s[48:49], -1
	s_and_b64 vcc, exec, s[46:47]
	s_cbranch_vccz .LBB0_780

; __device__ __forceinline__ unsigned xb_ld(unsigned* p)              { return __hip_atomic_load(p, __ATOMIC_RELAXED, __HIP_MEMORY_SCOPE_AGENT); }
; __device__ __forceinline__ void xcd_barrier_complete(unsigned* bar, unsigned x, unsigned& nloc, unsigned& nx) {
;     const unsigned G = gridDim.x * gridDim.y * gridDim.z;
;     unsigned sum, cnt, mine, sp = 0u;
;     for (;;) {
;         sum = 0u; cnt = 0u; mine = 0u;
; #pragma unroll
;         for (unsigned j = 0; j < 16; ++j) { const unsigned c = xb_ld(&bar[XB_XCNT(j)]); sum += c; cnt += (c > 0u) ? 1u : 0u; mine = (j == x) ? c : mine; }
;         if (sum == G) break;
;         __builtin_amdgcn_s_sleep(1);
;         if ((++sp & 255u) == 0u) { if (xb_ld(&bar[XB_TMO])) break; if (sp > XB_SPIN_CAP) { atomicAdd(&bar[XB_TMO], 1u); break; } }
.LBB0_828:
	global_load_dword v16, v17, s[20:21] sc1
	global_load_dword v1, v17, s[34:35] sc1
	global_load_dword v2, v17, s[40:41] sc1
	global_load_dword v3, v17, s[42:43] sc1
	global_load_dword v4, v17, s[44:45] sc1
	global_load_dword v5, v17, s[46:47] sc1
	global_load_dword v6, v17, s[48:49] sc1
	global_load_dword v7, v17, s[50:51] sc1
	global_load_dword v8, v17, s[52:53] sc1
	global_load_dword v9, v17, s[54:55] sc1
	global_load_dword v10, v17, s[56:57] sc1
	global_load_dword v11, v17, s[58:59] sc1
	global_load_dword v12, v17, s[60:61] sc1
	global_load_dword v13, v17, s[62:63] sc1
	global_load_dword v14, v17, s[64:65] sc1
	global_load_dword v15, v17, s[66:67] sc1
	s_mov_b64 s[68:69], -1
	s_mov_b64 s[70:71], -1
	s_waitcnt vmcnt(14)
	v_add_u32_e32 v18, v1, v16
	s_waitcnt vmcnt(13)
	v_add_u32_e32 v18, v18, v2
	s_waitcnt vmcnt(12)
	v_add_u32_e32 v18, v18, v3
	s_waitcnt vmcnt(11)
	v_add_u32_e32 v18, v18, v4
	s_waitcnt vmcnt(10)
	v_add_u32_e32 v18, v18, v5
	s_waitcnt vmcnt(9)
	v_add_u32_e32 v18, v18, v6
	s_waitcnt vmcnt(8)
	v_add_u32_e32 v18, v18, v7
	s_waitcnt vmcnt(7)
	v_add_u32_e32 v18, v18, v8
	s_waitcnt vmcnt(6)
	v_add_u32_e32 v18, v18, v9
	s_waitcnt vmcnt(5)
	v_add_u32_e32 v18, v18, v10
	s_waitcnt vmcnt(4)
	v_add_u32_e32 v18, v18, v11
	s_waitcnt vmcnt(3)
	v_add_u32_e32 v18, v18, v12
	s_waitcnt vmcnt(2)
	v_add_u32_e32 v18, v18, v13
	s_waitcnt vmcnt(1)
	v_add_u32_e32 v18, v18, v14
	s_waitcnt vmcnt(0)
	v_add_u32_e32 v18, v18, v15
	v_cmp_eq_u32_e32 vcc, s0, v18
	s_cbranch_vccnz .LBB0_827
	s_and_b32 s10, s1, 0xff
	s_cmp_eq_u32 s10, 0
	s_mov_b64 s[72:73], -1
	s_sleep 0
	s_cbranch_scc1 .LBB0_832
	s_and_b64 vcc, exec, s[72:73]
	s_cbranch_vccz .LBB0_827

; __device__ __forceinline__ unsigned xb_ld(unsigned* p)              { return __hip_atomic_load(p, __ATOMIC_RELAXED, __HIP_MEMORY_SCOPE_AGENT); }
; __device__ __forceinline__ unsigned xb_add(unsigned* p, unsigned v) { return __hip_atomic_fetch_add(p, v, __ATOMIC_RELAXED, __HIP_MEMORY_SCOPE_AGENT); }
; #define XB_SPIN(cond, bar) do { unsigned _sp = 0; while (cond) { __builtin_amdgcn_s_sleep(1); \
;     if ((++_sp & 255u) == 0u) { if (xb_ld(&(bar)[XB_TMO])) break; if (_sp > XB_SPIN_CAP) { atomicAdd(&(bar)[XB_TMO], 1u); break; } } } } while (0)
; __device__ __forceinline__ void xcd_barrier(const XcdBarrier& b) {
;     ...
;             const unsigned tg = og / nx;
;             if (og + 1u == (tg + 1u) * nx) xb_add(&bar[XB_TOPGEN], 1u);
;             else XB_SPIN(xb_ld(&bar[XB_TOPGEN]) == tg, bar);
;             __builtin_amdgcn_fence(__ATOMIC_ACQUIRE, "agent");
;             xb_add(&bar[XB_XGEN(b.x)], 1u);
;             asm volatile("s_waitcnt vmcnt(0)" ::: "memory");
;         } else {
;             XB_SPIN(xb_ld(&bar[XB_XGEN(b.x)]) == gen, bar);
;             __builtin_amdgcn_fence(__ATOMIC_ACQUIRE, "agent");
;             asm volatile("s_waitcnt vmcnt(0)" ::: "memory");
;         }
.LBB0_846:
	s_and_b32 s1, s0, 0xff
	s_mov_b64 s[48:49], -1
	s_cmp_lg_u32 s1, 0
	s_mov_b64 s[52:53], -1
	s_sleep 0
	s_cbranch_scc0 .LBB0_849
	s_and_b64 vcc, exec, s[52:53]
	s_cbranch_vccz .LBB0_845

; __device__ __forceinline__ unsigned xb_ld(unsigned* p)              { return __hip_atomic_load(p, __ATOMIC_RELAXED, __HIP_MEMORY_SCOPE_AGENT); }
; __device__ __forceinline__ void xcd_barrier_complete(unsigned* bar, unsigned x, unsigned& nloc, unsigned& nx) {
;     const unsigned G = gridDim.x * gridDim.y * gridDim.z;
;     unsigned sum, cnt, mine, sp = 0u;
;     for (;;) {
;         sum = 0u; cnt = 0u; mine = 0u;
; #pragma unroll
;         for (unsigned j = 0; j < 16; ++j) { const unsigned c = xb_ld(&bar[XB_XCNT(j)]); sum += c; cnt += (c > 0u) ? 1u : 0u; mine = (j == x) ? c : mine; }
;         if (sum == G) break;
;         __builtin_amdgcn_s_sleep(1);
;         if ((++sp & 255u) == 0u) { if (xb_ld(&bar[XB_TMO])) break; if (sp > XB_SPIN_CAP) { atomicAdd(&bar[XB_TMO], 1u); break; } }
.LBB0_918:
	global_load_dword v16, v17, s[14:15] sc1
	global_load_dword v1, v17, s[16:17] sc1
	global_load_dword v2, v17, s[18:19] sc1
	global_load_dword v3, v17, s[20:21] sc1
	global_load_dword v4, v17, s[34:35] sc1
	global_load_dword v5, v17, s[40:41] sc1
	global_load_dword v6, v17, s[42:43] sc1
	global_load_dword v7, v17, s[44:45] sc1
	global_load_dword v8, v17, s[46:47] sc1
	global_load_dword v9, v17, s[48:49] sc1
	global_load_dword v10, v17, s[50:51] sc1
	global_load_dword v11, v17, s[52:53] sc1
	global_load_dword v12, v17, s[54:55] sc1
	global_load_dword v13, v17, s[56:57] sc1
	global_load_dword v14, v17, s[58:59] sc1
	global_load_dword v15, v17, s[60:61] sc1
	s_mov_b64 s[62:63], -1
	s_mov_b64 s[64:65], -1
	s_waitcnt vmcnt(14)
	v_add_u32_e32 v18, v1, v16
	s_waitcnt vmcnt(13)
	v_add_u32_e32 v18, v18, v2
	s_waitcnt vmcnt(12)
	v_add_u32_e32 v18, v18, v3
	s_waitcnt vmcnt(11)
	v_add_u32_e32 v18, v18, v4
	s_waitcnt vmcnt(10)
	v_add_u32_e32 v18, v18, v5
	s_waitcnt vmcnt(9)
	v_add_u32_e32 v18, v18, v6
	s_waitcnt vmcnt(8)
	v_add_u32_e32 v18, v18, v7
	s_waitcnt vmcnt(7)
	v_add_u32_e32 v18, v18, v8
	s_waitcnt vmcnt(6)
	v_add_u32_e32 v18, v18, v9
	s_waitcnt vmcnt(5)
	v_add_u32_e32 v18, v18, v10
	s_waitcnt vmcnt(4)
	v_add_u32_e32 v18, v18, v11
	s_waitcnt vmcnt(3)
	v_add_u32_e32 v18, v18, v12
	s_waitcnt vmcnt(2)
	v_add_u32_e32 v18, v18, v13
	s_waitcnt vmcnt(1)
	v_add_u32_e32 v18, v18, v14
	s_waitcnt vmcnt(0)
	v_add_u32_e32 v18, v18, v15
	v_cmp_eq_u32_e32 vcc, s0, v18
	s_cbranch_vccnz .LBB0_917
	s_and_b32 s9, s1, 0xff
	s_cmp_eq_u32 s9, 0
	s_mov_b64 s[66:67], -1
	s_sleep 0
	s_cbranch_scc1 .LBB0_922
	s_and_b64 vcc, exec, s[66:67]
	s_cbranch_vccz .LBB0_917

; __device__ __forceinline__ unsigned xb_ld(unsigned* p)              { return __hip_atomic_load(p, __ATOMIC_RELAXED, __HIP_MEMORY_SCOPE_AGENT); }
; __device__ __forceinline__ unsigned xb_add(unsigned* p, unsigned v) { return __hip_atomic_fetch_add(p, v, __ATOMIC_RELAXED, __HIP_MEMORY_SCOPE_AGENT); }
; #define XB_SPIN(cond, bar) do { unsigned _sp = 0; while (cond) { __builtin_amdgcn_s_sleep(1); \
;     if ((++_sp & 255u) == 0u) { if (xb_ld(&(bar)[XB_TMO])) break; if (_sp > XB_SPIN_CAP) { atomicAdd(&(bar)[XB_TMO], 1u); break; } } } } while (0)
; __device__ __forceinline__ void xcd_barrier(const XcdBarrier& b) {
;     ...
;             const unsigned tg = og / nx;
;             if (og + 1u == (tg + 1u) * nx) xb_add(&bar[XB_TOPGEN], 1u);
;             else XB_SPIN(xb_ld(&bar[XB_TOPGEN]) == tg, bar);
;             __builtin_amdgcn_fence(__ATOMIC_ACQUIRE, "agent");
;             xb_add(&bar[XB_XGEN(b.x)], 1u);
;             asm volatile("s_waitcnt vmcnt(0)" ::: "memory");
;         } else {
;             XB_SPIN(xb_ld(&bar[XB_XGEN(b.x)]) == gen, bar);
;             __builtin_amdgcn_fence(__ATOMIC_ACQUIRE, "agent");
;             asm volatile("s_waitcnt vmcnt(0)" ::: "memory");
;         }
.LBB0_936:
	s_and_b32 s1, s0, 0xff
	s_mov_b64 s[42:43], -1
	s_cmp_lg_u32 s1, 0
	s_mov_b64 s[46:47], -1
	s_sleep 0
	s_cbranch_scc0 .LBB0_939
	s_and_b64 vcc, exec, s[46:47]
	s_cbranch_vccz .LBB0_935

; __device__ __forceinline__ unsigned xb_ld(unsigned* p)              { return __hip_atomic_load(p, __ATOMIC_RELAXED, __HIP_MEMORY_SCOPE_AGENT); }
; __device__ __forceinline__ unsigned xb_add(unsigned* p, unsigned v) { return __hip_atomic_fetch_add(p, v, __ATOMIC_RELAXED, __HIP_MEMORY_SCOPE_AGENT); }
; #define XB_SPIN(cond, bar) do { unsigned _sp = 0; while (cond) { __builtin_amdgcn_s_sleep(1); \
;     if ((++_sp & 255u) == 0u) { if (xb_ld(&(bar)[XB_TMO])) break; if (_sp > XB_SPIN_CAP) { atomicAdd(&(bar)[XB_TMO], 1u); break; } } } } while (0)
; __device__ __forceinline__ void xcd_barrier(const XcdBarrier& b) {
;     ...
;             const unsigned tg = og / nx;
;             if (og + 1u == (tg + 1u) * nx) xb_add(&bar[XB_TOPGEN], 1u);
;             else XB_SPIN(xb_ld(&bar[XB_TOPGEN]) == tg, bar);
;             __builtin_amdgcn_fence(__ATOMIC_ACQUIRE, "agent");
;             xb_add(&bar[XB_XGEN(b.x)], 1u);
;             asm volatile("s_waitcnt vmcnt(0)" ::: "memory");
;         } else {
;             XB_SPIN(xb_ld(&bar[XB_XGEN(b.x)]) == gen, bar);
;             __builtin_amdgcn_fence(__ATOMIC_ACQUIRE, "agent");
;             asm volatile("s_waitcnt vmcnt(0)" ::: "memory");
;         }
.LBB0_953:
	s_and_b32 s1, s0, 0xff
	s_cmp_lg_u32 s1, 0
	s_mov_b64 s[44:45], -1
	s_sleep 0
	s_cbranch_scc0 .LBB0_956
	s_mov_b64 s[46:47], -1
	s_and_b64 vcc, exec, s[44:45]
	s_cbranch_vccz .LBB0_952

; __device__ __forceinline__ unsigned xb_ld(unsigned* p)              { return __hip_atomic_load(p, __ATOMIC_RELAXED, __HIP_MEMORY_SCOPE_AGENT); }
; __device__ __forceinline__ void xcd_barrier_complete(unsigned* bar, unsigned x, unsigned& nloc, unsigned& nx) {
;     const unsigned G = gridDim.x * gridDim.y * gridDim.z;
;     unsigned sum, cnt, mine, sp = 0u;
;     for (;;) {
;         sum = 0u; cnt = 0u; mine = 0u;
; #pragma unroll
;         for (unsigned j = 0; j < 16; ++j) { const unsigned c = xb_ld(&bar[XB_XCNT(j)]); sum += c; cnt += (c > 0u) ? 1u : 0u; mine = (j == x) ? c : mine; }
;         if (sum == G) break;
;         __builtin_amdgcn_s_sleep(1);
;         if ((++sp & 255u) == 0u) { if (xb_ld(&bar[XB_TMO])) break; if (sp > XB_SPIN_CAP) { atomicAdd(&bar[XB_TMO], 1u); break; } }
.LBB0_1139:
	global_load_dword v16, v17, s[4:5] sc1
	global_load_dword v1, v17, s[6:7] sc1
	global_load_dword v2, v17, s[8:9] sc1
	global_load_dword v3, v17, s[12:13] sc1
	global_load_dword v4, v17, s[14:15] sc1
	global_load_dword v5, v17, s[16:17] sc1
	global_load_dword v6, v17, s[18:19] sc1
	global_load_dword v7, v17, s[20:21] sc1
	global_load_dword v8, v17, s[28:29] sc1
	global_load_dword v9, v17, s[34:35] sc1
	global_load_dword v10, v17, s[40:41] sc1
	global_load_dword v11, v17, s[42:43] sc1
	global_load_dword v12, v17, s[44:45] sc1
	global_load_dword v13, v17, s[46:47] sc1
	global_load_dword v14, v17, s[48:49] sc1
	global_load_dword v15, v17, s[50:51] sc1
	s_mov_b64 s[52:53], -1
	s_mov_b64 s[54:55], -1
	s_waitcnt vmcnt(14)
	v_add_u32_e32 v18, v1, v16
	s_waitcnt vmcnt(13)
	v_add_u32_e32 v18, v18, v2
	s_waitcnt vmcnt(12)
	v_add_u32_e32 v18, v18, v3
	s_waitcnt vmcnt(11)
	v_add_u32_e32 v18, v18, v4
	s_waitcnt vmcnt(10)
	v_add_u32_e32 v18, v18, v5
	s_waitcnt vmcnt(9)
	v_add_u32_e32 v18, v18, v6
	s_waitcnt vmcnt(8)
	v_add_u32_e32 v18, v18, v7
	s_waitcnt vmcnt(7)
	v_add_u32_e32 v18, v18, v8
	s_waitcnt vmcnt(6)
	v_add_u32_e32 v18, v18, v9
	s_waitcnt vmcnt(5)
	v_add_u32_e32 v18, v18, v10
	s_waitcnt vmcnt(4)
	v_add_u32_e32 v18, v18, v11
	s_waitcnt vmcnt(3)
	v_add_u32_e32 v18, v18, v12
	s_waitcnt vmcnt(2)
	v_add_u32_e32 v18, v18, v13
	s_waitcnt vmcnt(1)
	v_add_u32_e32 v18, v18, v14
	s_waitcnt vmcnt(0)
	v_add_u32_e32 v18, v18, v15
	v_cmp_eq_u32_e32 vcc, s10, v18
	s_cbranch_vccnz .LBB0_1138
	s_and_b32 s31, s11, 0xff
	s_cmp_eq_u32 s31, 0
	s_mov_b64 s[56:57], -1
	s_sleep 0
	s_cbranch_scc1 .LBB0_1143
	s_and_b64 vcc, exec, s[56:57]
	s_cbranch_vccz .LBB0_1138

; __device__ __forceinline__ unsigned xb_ld(unsigned* p)              { return __hip_atomic_load(p, __ATOMIC_RELAXED, __HIP_MEMORY_SCOPE_AGENT); }
; __device__ __forceinline__ unsigned xb_add(unsigned* p, unsigned v) { return __hip_atomic_fetch_add(p, v, __ATOMIC_RELAXED, __HIP_MEMORY_SCOPE_AGENT); }
; #define XB_SPIN(cond, bar) do { unsigned _sp = 0; while (cond) { __builtin_amdgcn_s_sleep(1); \
;     if ((++_sp & 255u) == 0u) { if (xb_ld(&(bar)[XB_TMO])) break; if (_sp > XB_SPIN_CAP) { atomicAdd(&(bar)[XB_TMO], 1u); break; } } } } while (0)
; __device__ __forceinline__ void xcd_barrier(const XcdBarrier& b) {
;     ...
;             const unsigned tg = og / nx;
;             if (og + 1u == (tg + 1u) * nx) xb_add(&bar[XB_TOPGEN], 1u);
;             else XB_SPIN(xb_ld(&bar[XB_TOPGEN]) == tg, bar);
;             __builtin_amdgcn_fence(__ATOMIC_ACQUIRE, "agent");
;             xb_add(&bar[XB_XGEN(b.x)], 1u);
;             asm volatile("s_waitcnt vmcnt(0)" ::: "memory");
;         } else {
;             XB_SPIN(xb_ld(&bar[XB_XGEN(b.x)]) == gen, bar);
;             __builtin_amdgcn_fence(__ATOMIC_ACQUIRE, "agent");
;             asm volatile("s_waitcnt vmcnt(0)" ::: "memory");
;         }
.LBB0_1158:
	s_and_b32 s18, s28, 0xff
	s_mov_b64 s[16:17], -1
	s_cmp_lg_u32 s18, 0
	s_mov_b64 s[20:21], -1
	s_sleep 0
	s_cbranch_scc0 .LBB0_1161
	s_and_b64 vcc, exec, s[20:21]
	s_cbranch_vccz .LBB0_1157

; __device__ __forceinline__ unsigned xb_ld(unsigned* p)              { return __hip_atomic_load(p, __ATOMIC_RELAXED, __HIP_MEMORY_SCOPE_AGENT); }
; __device__ __forceinline__ unsigned xb_add(unsigned* p, unsigned v) { return __hip_atomic_fetch_add(p, v, __ATOMIC_RELAXED, __HIP_MEMORY_SCOPE_AGENT); }
; #define XB_SPIN(cond, bar) do { unsigned _sp = 0; while (cond) { __builtin_amdgcn_s_sleep(1); \
;     if ((++_sp & 255u) == 0u) { if (xb_ld(&(bar)[XB_TMO])) break; if (_sp > XB_SPIN_CAP) { atomicAdd(&(bar)[XB_TMO], 1u); break; } } } } while (0)
; __device__ __forceinline__ void xcd_barrier(const XcdBarrier& b) {
;     ...
;             const unsigned tg = og / nx;
;             if (og + 1u == (tg + 1u) * nx) xb_add(&bar[XB_TOPGEN], 1u);
;             else XB_SPIN(xb_ld(&bar[XB_TOPGEN]) == tg, bar);
;             __builtin_amdgcn_fence(__ATOMIC_ACQUIRE, "agent");
;             xb_add(&bar[XB_XGEN(b.x)], 1u);
;             asm volatile("s_waitcnt vmcnt(0)" ::: "memory");
;         } else {
;             XB_SPIN(xb_ld(&bar[XB_XGEN(b.x)]) == gen, bar);
;             __builtin_amdgcn_fence(__ATOMIC_ACQUIRE, "agent");
;             asm volatile("s_waitcnt vmcnt(0)" ::: "memory");
;         }
.LBB0_1175:
	s_and_b32 s16, s28, 0xff
	s_cmp_lg_u32 s16, 0
	s_mov_b64 s[18:19], -1
	s_sleep 0
	s_cbranch_scc0 .LBB0_1178
	s_mov_b64 s[20:21], -1
	s_and_b64 vcc, exec, s[18:19]
	s_cbranch_vccz .LBB0_1174
